# ffn2_weights moved from attention WGs to scan WGs
# speedup vs baseline: 1.0400x; 1.0088x over previous
; #define LAS __attribute__((address_space(3)))
;     __device__ __forceinline__ const float* in(int i) const { return (const float*)ptr(i); }
;     __device__ __forceinline__ unsigned char* ws() const { return (unsigned char*)ptr(37); }
; #define ws (p.ws())
; __device__ __forceinline__ void ffn2_weights(const Ctx& p, LAS unsigned char* lds) {
;     const int tid = threadIdx.x, lane = tid & 63, wave = __builtin_amdgcn_readfirstlane(tid >> 6);
;     unsigned char* ws = p.ws();
;     LAS float* scr = (LAS float*)(lds + wave * 16384);
;     constexpr int I7 = 16 * 176, I8 = 44 * 32;
;     __syncthreads();
;     for (int it = ((int)blockIdx.x - 128) * 8 + wave; it < I7 + I8; it += 128 * 8) {
;         int r = it;
;         if (r < I7) { const int kb = r / 176, nb = r % 176; transpose_item(p.in(33), DM, NFF, (bf16_t*)(ws + WS_W3T), 64 * kb, 32 * nb, map_w1(32 * nb), scr, lane); continue; } r -= I7;
;         { const int kb = r / 32, nb = r % 32; transpose_item(p.in(34), DFF, DM, (bf16_t*)(ws + WS_W4T), 64 * kb, 32 * nb, 32 * nb, scr, lane); }
;     }
; }
; __device__ __forceinline__ void phase_mixer(const Ctx& p, LAS unsigned char* lds) {
;     if (blockIdx.x < 128) scan_unit(p, blockIdx.x >> 2, blockIdx.x & 3, lds);
;     else { const int u0 = (blockIdx.x - 128) * 2; scan_unit(p, 32 + (u0 >> 2), u0 & 3, lds); scan_unit(p, 32 + ((u0 + 1) >> 2), (u0 + 1) & 3, lds); }
;     if (blockIdx.x < 128) return;
.LBB0_1804:
	s_branch .LBB0_1819
.Lscan_ffn2w:
	v_and_b32_e32 v132, 63, v180
	v_lshlrev_b32_e32 v2, 3, v180
	v_and_b32_e32 v140, 56, v2
	v_lshlrev_b32_e32 v138, 1, v140
	s_add_i32 s2, 0, 0x23528
	v_mov_b32_e32 v0, s2
	ds_read_b64 v[0:1], v0
	v_readfirstlane_b32 s2, v180
	s_lshr_b32 s4, s2, 6
	s_lshl_b32 s5, s28, 3
	s_add_i32 s5, s5, s4
	s_mov_b32 s7, s5
	s_mov_b32 s6, 0
	s_waitcnt lgkmcnt(0)
	v_readfirstlane_b32 s2, v0
	v_readfirstlane_b32 s3, v1
	s_cmpk_gt_i32 s7, 0x107f
	s_barrier
	s_cbranch_scc1 .LBB0_1819
	v_mov_b32_e32 v139, 0
	s_lshl_b32 s4, s4, 14
	v_lshrrev_b32_e32 v3, 3, v132
	v_lshl_add_u64 v[6:7], s[2:3], 0, v[138:139]
	s_mov_b64 s[2:3], 0x2a00000
	s_add_i32 s4, s4, 0
	v_lshrrev_b32_e32 v0, 5, v132
	v_and_b32_e32 v8, 31, v180
	v_mul_u32_u24_e32 v1, 0x84, v140
	v_lshl_add_u64 v[4:5], v[6:7], 0, s[2:3]
	v_lshlrev_b32_e32 v9, 2, v3
	s_mov_b64 s[2:3], 0x1f00000
	v_lshl_add_u32 v2, v8, 2, s4
	s_movk_i32 s8, 0x84
	v_add3_u32 v10, s4, v1, v9
	v_or_b32_e32 v11, 8, v3
	v_or_b32_e32 v12, 16, v3
	v_or_b32_e32 v13, 24, v3
	v_lshl_add_u64 v[6:7], v[6:7], 0, s[2:3]
	v_mov_b32_e32 v1, v0
	s_add_i32 s9, 0, 0x23510
	s_add_i32 s10, 0, 0x23508
	s_movk_i32 s11, 0x5800
	v_lshlrev_b32_e32 v138, 2, v8
	s_branch .LBB0_1807
